# GEMM K-loops: the barrier ending each MFMA block issued one MFMA before the end of the block (register-only MFMA crosses the barrier)
# speedup vs baseline: 1.0264x; 1.0071x over previous
; #define PG8_STAGE(bufoff, gbase, voff) do { _Pragma("unroll") for (int _i = 0; _i < 2; ++_i) \
;         __builtin_amdgcn_global_load_lds((const unsigned*)((const char*)(gbase) + (voff)[_i]), (PG8_LAS unsigned*)(lds + (bufoff) + ldsw + _i * 8192), 16, 0, 0); } while (0)
; #define PG8_LDA(dst, b, h) do { _Pragma("unroll") for (int m = 0; m < 4; ++m) _Pragma("unroll") for (int k = 0; k < 2; ++k) dst[m][k] = *(const PG8_LAS bf16x8*)(lds + PG8_SA(b, h) + aoff + m * 2048 + k * 1024); } while (0)
; #define PG8_LDB(dst, b, h) do { _Pragma("unroll") for (int n = 0; n < 2; ++n) _Pragma("unroll") for (int k = 0; k < 2; ++k) dst[n][k] = *(const PG8_LAS bf16x8*)(lds + PG8_SB(b, h) + boff + n * 2048 + k * 1024); } while (0)
; #define PG8_MMA(ai, bj, At, Bt) do { __builtin_amdgcn_s_setprio(1); _Pragma("unroll") for (int m = 0; m < 4; ++m) _Pragma("unroll") for (int n = 0; n < 2; ++n) _Pragma("unroll") for (int k = 0; k < 2; ++k) \
;         acc[ai][bj][m][n] = __builtin_amdgcn_mfma_f32_16x16x32_bf16(Bt[n][k], At[m][k], acc[ai][bj][m][n], 0, 0, 0); __builtin_amdgcn_s_setprio(0); } while (0)
; #define PG8_WAIT_V(n) asm volatile("s_waitcnt vmcnt(" #n ")" ::: "memory")
; #define PG8_BAR __builtin_amdgcn_s_barrier()
; template <class Epi, class Sched, bool ALIGN_EPI = false, bool SP2 = false>
; __device__ __forceinline__ void gemm_phase(PG8_LAS unsigned char* lds, const Gemm g, const Sched& S, const Epi& E) {
;     ...
;         for (int t = 0; t < nt; t += 2) {
;             const bool last = (t == nt - 2);
;             const char* a1 = cA + (size_t)(t + 1) * kstep;
;             const char* a2 = last ? nA : cA + (size_t)(t + 2) * kstep; const char* b2 = last ? nB : cB + (size_t)(t + 2) * kstep;
;             const char* a3 = a2 + kstep; const char* b3 = b2 + kstep;
;             if (last && has_next) S.a_ready(nxt);
;             if constexpr (SP2) {
;             PG8_LDB(B0, 0, 0); PG8_LDB(B1, 0, 1); PG8_SCHED; PG8_LDA(At, 0, 0); PG8_STAGE(PG8_SA(1, 1), a1 + hstep, voffA);
;             PG8_WAIT_V(8); PG8_WAIT_L(0); PG8_BAR; PG8_MMA(0, 0, At, B0); PG8_MMA(0, 1, At, B1); PG8_BAR; PG8_SCHED;
;             PG8_LDA(At, 0, 1); PG8_STAGE(PG8_SB(0, 0), b2, voffB); PG8_STAGE(PG8_SB(0, 1), b2 + hstep, voffB); PG8_STAGE(PG8_SA(0, 0), a2, voffA);
;             PG8_WAIT_V(8); PG8_WAIT_L(0); PG8_BAR; PG8_MMA(1, 0, At, B0); PG8_MMA(1, 1, At, B1); PG8_BAR; PG8_SCHED;
.LBB0_165:
	s_add_u32 s16, s8, 0xfffc0080
	s_addc_u32 s17, s9, -1
	s_add_i32 s18, 0, 0x10000
	s_cmp_eq_u32 s55, 12
	s_cselect_b32 s43, s14, s17
	s_cselect_b32 s42, s15, s16
	v_add_u32_e32 v0, s18, v194
	s_cselect_b32 s41, s13, s54
	s_cselect_b32 s40, s25, s53
	s_add_i32 s19, 0, 0x14000
	ds_read_b128 v[136:139], v0
	ds_read_b128 v[140:143], v0 offset:1024
	ds_read_b128 v[144:147], v0 offset:2048
	ds_read_b128 v[148:151], v0 offset:3072
	v_add_u32_e32 v0, s19, v194
	ds_read_b128 v[152:155], v0
	ds_read_b128 v[186:189], v0 offset:1024
	ds_read_b128 v[190:193], v0 offset:2048
	ds_read_b128 v[198:201], v0 offset:3072
	v_lshl_add_u64 v[2:3], s[8:9], 0, v[182:183]
	s_add_i32 m0, s45, 0xc000
	ds_read_b128 v[210:213], v196
	ds_read_b128 v[214:217], v196 offset:1024
	ds_read_b128 v[218:221], v196 offset:2048
	ds_read_b128 v[222:225], v196 offset:3072
	ds_read_b128 v[226:229], v196 offset:4096
	ds_read_b128 v[230:233], v196 offset:5120
	ds_read_b128 v[234:237], v196 offset:6144
	ds_read_b128 v[238:241], v196 offset:7168
	global_load_lds_dwordx4 v[2:3], off
	v_lshl_add_u64 v[2:3], s[8:9], 0, v[184:185]
	s_add_i32 m0, s45, 0xe000
	s_nop 0
	global_load_lds_dwordx4 v[2:3], off
	s_waitcnt vmcnt(8)
	s_waitcnt lgkmcnt(0)
	s_barrier
	s_setprio 1
	s_waitcnt lgkmcnt(0)
	v_mfma_f32_16x16x32_bf16 v[132:135], v[136:139], v[210:213], v[132:135]
	v_mfma_f32_16x16x32_bf16 v[128:131], v[144:147], v[210:213], v[128:131]
	v_mfma_f32_16x16x32_bf16 v[124:127], v[136:139], v[218:221], v[124:127]
	v_mfma_f32_16x16x32_bf16 v[120:123], v[144:147], v[218:221], v[120:123]
	v_mfma_f32_16x16x32_bf16 v[116:119], v[136:139], v[226:229], v[116:119]
	v_mfma_f32_16x16x32_bf16 v[112:115], v[144:147], v[226:229], v[112:115]
	v_mfma_f32_16x16x32_bf16 v[108:111], v[136:139], v[234:237], v[108:111]
	v_mfma_f32_16x16x32_bf16 v[104:107], v[144:147], v[234:237], v[104:107]
	v_mfma_f32_16x16x32_bf16 v[132:135], v[140:143], v[214:217], v[132:135]
	v_mfma_f32_16x16x32_bf16 v[128:131], v[148:151], v[214:217], v[128:131]
	v_mfma_f32_16x16x32_bf16 v[124:127], v[140:143], v[222:225], v[124:127]
	v_mfma_f32_16x16x32_bf16 v[120:123], v[148:151], v[222:225], v[120:123]
	v_mfma_f32_16x16x32_bf16 v[116:119], v[140:143], v[230:233], v[116:119]
	v_mfma_f32_16x16x32_bf16 v[112:115], v[148:151], v[230:233], v[112:115]
	v_mfma_f32_16x16x32_bf16 v[108:111], v[140:143], v[238:241], v[108:111]
	v_mfma_f32_16x16x32_bf16 v[104:107], v[148:151], v[238:241], v[104:107]
	s_setprio 0
	s_setprio 1
	v_mfma_f32_16x16x32_bf16 v[84:87], v[152:155], v[210:213], v[84:87]
	v_mfma_f32_16x16x32_bf16 v[76:79], v[190:193], v[210:213], v[76:79]
	v_mfma_f32_16x16x32_bf16 v[68:71], v[152:155], v[218:221], v[68:71]
	v_mfma_f32_16x16x32_bf16 v[64:67], v[190:193], v[218:221], v[64:67]
	v_mfma_f32_16x16x32_bf16 v[52:55], v[152:155], v[226:229], v[52:55]
	v_mfma_f32_16x16x32_bf16 v[48:51], v[190:193], v[226:229], v[48:51]
	v_mfma_f32_16x16x32_bf16 v[44:47], v[152:155], v[234:237], v[44:47]
	v_mfma_f32_16x16x32_bf16 v[40:43], v[190:193], v[234:237], v[40:43]
	v_mfma_f32_16x16x32_bf16 v[84:87], v[186:189], v[214:217], v[84:87]
	v_mfma_f32_16x16x32_bf16 v[76:79], v[198:201], v[214:217], v[76:79]
	v_mfma_f32_16x16x32_bf16 v[68:71], v[186:189], v[222:225], v[68:71]
	v_mfma_f32_16x16x32_bf16 v[64:67], v[198:201], v[222:225], v[64:67]
	v_mfma_f32_16x16x32_bf16 v[52:55], v[186:189], v[230:233], v[52:55]
	v_mfma_f32_16x16x32_bf16 v[48:51], v[198:201], v[230:233], v[48:51]
	v_mfma_f32_16x16x32_bf16 v[44:47], v[186:189], v[238:241], v[44:47]
	s_barrier
	v_mfma_f32_16x16x32_bf16 v[40:43], v[198:201], v[238:241], v[40:43]
	s_setprio 0
	s_add_i32 s16, s18, s44
	v_lshl_add_u64 v[2:3], s[40:41], 0, v[162:163]
	s_mov_b32 m0, s16
	ds_read_b128 v[210:213], v196 offset:16384
	ds_read_b128 v[214:217], v196 offset:17408
	ds_read_b128 v[218:221], v196 offset:18432
	ds_read_b128 v[222:225], v196 offset:19456
	ds_read_b128 v[226:229], v196 offset:20480
	ds_read_b128 v[230:233], v196 offset:21504
	ds_read_b128 v[234:237], v196 offset:22528
	ds_read_b128 v[238:241], v196 offset:23552
	global_load_lds_dwordx4 v[2:3], off
	s_add_i32 m0, s16, 0x2000
	s_add_u32 s16, s40, 0x40000
	v_lshl_add_u64 v[156:157], s[40:41], 0, v[158:159]
	s_addc_u32 s17, s41, 0
	s_add_i32 s18, s19, s44
	global_load_lds_dwordx4 v[156:157], off
	v_lshl_add_u64 v[242:243], s[16:17], 0, v[162:163]
	s_mov_b32 m0, s18
	v_lshl_add_u64 v[244:245], s[42:43], 0, v[160:161]
	global_load_lds_dwordx4 v[242:243], off
	v_lshl_add_u64 v[242:243], s[16:17], 0, v[158:159]
	s_add_i32 m0, s18, 0x2000
	s_nop 0
	global_load_lds_dwordx4 v[242:243], off
	v_lshl_add_u64 v[242:243], s[42:43], 0, v[178:179]
	s_waitcnt vmcnt(6)
	s_waitcnt lgkmcnt(0)
	s_barrier
; #define PG8_STAGE(bufoff, gbase, voff) do { _Pragma("unroll") for (int _i = 0; _i < 2; ++_i) \
;         __builtin_amdgcn_global_load_lds((const unsigned*)((const char*)(gbase) + (voff)[_i]), (PG8_LAS unsigned*)(lds + (bufoff) + ldsw + _i * 8192), 16, 0, 0); } while (0)
; #define PG8_LDA(dst, b, h) do { _Pragma("unroll") for (int m = 0; m < 4; ++m) _Pragma("unroll") for (int k = 0; k < 2; ++k) dst[m][k] = *(const PG8_LAS bf16x8*)(lds + PG8_SA(b, h) + aoff + m * 2048 + k * 1024); } while (0)
; #define PG8_LDB(dst, b, h) do { _Pragma("unroll") for (int n = 0; n < 2; ++n) _Pragma("unroll") for (int k = 0; k < 2; ++k) dst[n][k] = *(const PG8_LAS bf16x8*)(lds + PG8_SB(b, h) + boff + n * 2048 + k * 1024); } while (0)
; #define PG8_MMA(ai, bj, At, Bt) do { __builtin_amdgcn_s_setprio(1); _Pragma("unroll") for (int m = 0; m < 4; ++m) _Pragma("unroll") for (int n = 0; n < 2; ++n) _Pragma("unroll") for (int k = 0; k < 2; ++k) \
;         acc[ai][bj][m][n] = __builtin_amdgcn_mfma_f32_16x16x32_bf16(Bt[n][k], At[m][k], acc[ai][bj][m][n], 0, 0, 0); __builtin_amdgcn_s_setprio(0); } while (0)
; #define PG8_WAIT_V(n) asm volatile("s_waitcnt vmcnt(" #n ")" ::: "memory")
; #define PG8_WAIT_L(n) asm volatile("s_waitcnt lgkmcnt(" #n ")" ::: "memory")
; #define PG8_BAR __builtin_amdgcn_s_barrier()
; #define PG8_SCHED __builtin_amdgcn_sched_barrier(0)
; template <class Epi, class Sched, bool ALIGN_EPI = false, bool SP2 = false>
; __device__ __forceinline__ void gemm_phase(PG8_LAS unsigned char* lds, const Gemm g, const Sched& S, const Epi& E) {
;     ...
;             PG8_WAIT_V(8); PG8_WAIT_L(0); PG8_BAR; PG8_MMA(0, 0, At, B0); PG8_MMA(0, 1, At, B1); PG8_BAR; PG8_SCHED;
;             PG8_LDA(At, 0, 1); PG8_STAGE(PG8_SB(0, 0), b2, voffB); PG8_STAGE(PG8_SB(0, 1), b2 + hstep, voffB); PG8_STAGE(PG8_SA(0, 0), a2, voffA);
;             PG8_WAIT_V(8); PG8_WAIT_L(0); PG8_BAR; PG8_MMA(1, 0, At, B0); PG8_MMA(1, 1, At, B1); PG8_BAR; PG8_SCHED;
;             PG8_LDB(B0, 1, 0); PG8_LDB(B1, 1, 1); PG8_SCHED; PG8_LDA(At, 1, 0); PG8_STAGE(PG8_SA(0, 1), a2 + hstep, voffA);
;             PG8_WAIT_V(8); PG8_WAIT_L(0); PG8_BAR; PG8_MMA(0, 0, At, B0); PG8_MMA(0, 1, At, B1); PG8_BAR; PG8_SCHED;
	s_setprio 1
	s_waitcnt lgkmcnt(0)
	v_mfma_f32_16x16x32_bf16 v[100:103], v[136:139], v[210:213], v[100:103]
	v_mfma_f32_16x16x32_bf16 v[96:99], v[144:147], v[210:213], v[96:99]
	v_mfma_f32_16x16x32_bf16 v[92:95], v[136:139], v[218:221], v[92:95]
	s_mov_b32 m0, s45
	v_mfma_f32_16x16x32_bf16 v[88:91], v[144:147], v[218:221], v[88:91]
	global_load_lds_dwordx4 v[242:243], off
	v_mfma_f32_16x16x32_bf16 v[80:83], v[136:139], v[226:229], v[80:83]
	v_mfma_f32_16x16x32_bf16 v[72:75], v[144:147], v[226:229], v[72:75]
	v_mfma_f32_16x16x32_bf16 v[60:63], v[136:139], v[234:237], v[60:63]
	v_mfma_f32_16x16x32_bf16 v[56:59], v[144:147], v[234:237], v[56:59]
	v_mfma_f32_16x16x32_bf16 v[100:103], v[140:143], v[214:217], v[100:103]
	v_mfma_f32_16x16x32_bf16 v[96:99], v[148:151], v[214:217], v[96:99]
	v_mfma_f32_16x16x32_bf16 v[92:95], v[140:143], v[222:225], v[92:95]
	s_mov_b32 m0, s46
	v_mfma_f32_16x16x32_bf16 v[88:91], v[148:151], v[222:225], v[88:91]
	global_load_lds_dwordx4 v[244:245], off
	v_mfma_f32_16x16x32_bf16 v[80:83], v[140:143], v[230:233], v[80:83]
	v_mfma_f32_16x16x32_bf16 v[72:75], v[148:151], v[230:233], v[72:75]
	v_mfma_f32_16x16x32_bf16 v[60:63], v[140:143], v[238:241], v[60:63]
	v_mfma_f32_16x16x32_bf16 v[56:59], v[148:151], v[238:241], v[56:59]
	s_setprio 0
	s_setprio 1
	v_mfma_f32_16x16x32_bf16 v[36:39], v[152:155], v[210:213], v[36:39]
	v_mfma_f32_16x16x32_bf16 v[32:35], v[190:193], v[210:213], v[32:35]
	v_mfma_f32_16x16x32_bf16 v[28:31], v[152:155], v[218:221], v[28:31]
	v_mfma_f32_16x16x32_bf16 v[24:27], v[190:193], v[218:221], v[24:27]
	v_mfma_f32_16x16x32_bf16 v[20:23], v[152:155], v[226:229], v[20:23]
	v_mfma_f32_16x16x32_bf16 v[16:19], v[190:193], v[226:229], v[16:19]
	v_mfma_f32_16x16x32_bf16 v[12:15], v[152:155], v[234:237], v[12:15]
	v_mfma_f32_16x16x32_bf16 v[8:11], v[190:193], v[234:237], v[8:11]
	v_mfma_f32_16x16x32_bf16 v[36:39], v[186:189], v[214:217], v[36:39]
	v_mfma_f32_16x16x32_bf16 v[32:35], v[198:201], v[214:217], v[32:35]
	v_mfma_f32_16x16x32_bf16 v[28:31], v[186:189], v[222:225], v[28:31]
	v_mfma_f32_16x16x32_bf16 v[24:27], v[198:201], v[222:225], v[24:27]
	v_mfma_f32_16x16x32_bf16 v[20:23], v[186:189], v[230:233], v[20:23]
	v_mfma_f32_16x16x32_bf16 v[16:19], v[198:201], v[230:233], v[16:19]
	v_mfma_f32_16x16x32_bf16 v[12:15], v[186:189], v[238:241], v[12:15]
	s_barrier
	v_mfma_f32_16x16x32_bf16 v[8:11], v[198:201], v[238:241], v[8:11]
	s_setprio 0
	s_add_i32 s18, 0, 0x18000
	v_add_u32_e32 v0, s18, v194
	ds_read_b128 v[136:139], v0
	ds_read_b128 v[140:143], v0 offset:1024
	ds_read_b128 v[144:147], v0 offset:2048
	ds_read_b128 v[148:151], v0 offset:3072
	v_add_u32_e32 v0, s33, v194
	ds_read_b128 v[152:155], v0
	ds_read_b128 v[186:189], v0 offset:1024
	ds_read_b128 v[190:193], v0 offset:2048
	ds_read_b128 v[198:201], v0 offset:3072
	s_add_u32 s16, s42, 0x40000
	s_addc_u32 s17, s43, 0
	s_mov_b32 m0, s47
	v_lshl_add_u64 v[246:247], s[16:17], 0, v[178:179]
	ds_read_b128 v[210:213], v196 offset:32768
	ds_read_b128 v[214:217], v196 offset:33792
	ds_read_b128 v[218:221], v196 offset:34816
	ds_read_b128 v[222:225], v196 offset:35840
	ds_read_b128 v[226:229], v196 offset:36864
	ds_read_b128 v[230:233], v196 offset:37888
	ds_read_b128 v[234:237], v196 offset:38912
	ds_read_b128 v[238:241], v196 offset:39936
	global_load_lds_dwordx4 v[246:247], off
	v_lshl_add_u64 v[246:247], s[16:17], 0, v[160:161]
	s_mov_b32 m0, s48
	s_nop 0
	global_load_lds_dwordx4 v[246:247], off
	s_waitcnt vmcnt(8)
	s_waitcnt lgkmcnt(0)
	s_barrier
	s_setprio 1
	s_waitcnt lgkmcnt(0)
	v_mfma_f32_16x16x32_bf16 v[132:135], v[136:139], v[210:213], v[132:135]
	v_mfma_f32_16x16x32_bf16 v[128:131], v[144:147], v[210:213], v[128:131]
	v_mfma_f32_16x16x32_bf16 v[124:127], v[136:139], v[218:221], v[124:127]
	v_mfma_f32_16x16x32_bf16 v[120:123], v[144:147], v[218:221], v[120:123]
	v_mfma_f32_16x16x32_bf16 v[116:119], v[136:139], v[226:229], v[116:119]
	v_mfma_f32_16x16x32_bf16 v[112:115], v[144:147], v[226:229], v[112:115]
	v_mfma_f32_16x16x32_bf16 v[108:111], v[136:139], v[234:237], v[108:111]
	v_mfma_f32_16x16x32_bf16 v[104:107], v[144:147], v[234:237], v[104:107]
	v_mfma_f32_16x16x32_bf16 v[132:135], v[140:143], v[214:217], v[132:135]
	v_mfma_f32_16x16x32_bf16 v[128:131], v[148:151], v[214:217], v[128:131]
	v_mfma_f32_16x16x32_bf16 v[124:127], v[140:143], v[222:225], v[124:127]
	v_mfma_f32_16x16x32_bf16 v[120:123], v[148:151], v[222:225], v[120:123]
	v_mfma_f32_16x16x32_bf16 v[116:119], v[140:143], v[230:233], v[116:119]
	v_mfma_f32_16x16x32_bf16 v[112:115], v[148:151], v[230:233], v[112:115]
	v_mfma_f32_16x16x32_bf16 v[108:111], v[140:143], v[238:241], v[108:111]
	v_mfma_f32_16x16x32_bf16 v[104:107], v[148:151], v[238:241], v[104:107]
	s_setprio 0
	s_setprio 1
	v_mfma_f32_16x16x32_bf16 v[84:87], v[152:155], v[210:213], v[84:87]
	v_mfma_f32_16x16x32_bf16 v[76:79], v[190:193], v[210:213], v[76:79]
	v_mfma_f32_16x16x32_bf16 v[68:71], v[152:155], v[218:221], v[68:71]
	v_mfma_f32_16x16x32_bf16 v[64:67], v[190:193], v[218:221], v[64:67]
	v_mfma_f32_16x16x32_bf16 v[52:55], v[152:155], v[226:229], v[52:55]
	v_mfma_f32_16x16x32_bf16 v[48:51], v[190:193], v[226:229], v[48:51]
	v_mfma_f32_16x16x32_bf16 v[44:47], v[152:155], v[234:237], v[44:47]
	v_mfma_f32_16x16x32_bf16 v[40:43], v[190:193], v[234:237], v[40:43]
	v_mfma_f32_16x16x32_bf16 v[84:87], v[186:189], v[214:217], v[84:87]
	v_mfma_f32_16x16x32_bf16 v[76:79], v[198:201], v[214:217], v[76:79]
	v_mfma_f32_16x16x32_bf16 v[68:71], v[186:189], v[222:225], v[68:71]
	v_mfma_f32_16x16x32_bf16 v[64:67], v[198:201], v[222:225], v[64:67]
	v_mfma_f32_16x16x32_bf16 v[52:55], v[186:189], v[230:233], v[52:55]
	v_mfma_f32_16x16x32_bf16 v[48:51], v[198:201], v[230:233], v[48:51]
	v_mfma_f32_16x16x32_bf16 v[44:47], v[186:189], v[238:241], v[44:47]
	s_barrier
; #define PG8_STAGE(bufoff, gbase, voff) do { _Pragma("unroll") for (int _i = 0; _i < 2; ++_i) \
;         __builtin_amdgcn_global_load_lds((const unsigned*)((const char*)(gbase) + (voff)[_i]), (PG8_LAS unsigned*)(lds + (bufoff) + ldsw + _i * 8192), 16, 0, 0); } while (0)
; #define PG8_LDA(dst, b, h) do { _Pragma("unroll") for (int m = 0; m < 4; ++m) _Pragma("unroll") for (int k = 0; k < 2; ++k) dst[m][k] = *(const PG8_LAS bf16x8*)(lds + PG8_SA(b, h) + aoff + m * 2048 + k * 1024); } while (0)
; #define PG8_LDB(dst, b, h) do { _Pragma("unroll") for (int n = 0; n < 2; ++n) _Pragma("unroll") for (int k = 0; k < 2; ++k) dst[n][k] = *(const PG8_LAS bf16x8*)(lds + PG8_SB(b, h) + boff + n * 2048 + k * 1024); } while (0)
; #define PG8_MMA(ai, bj, At, Bt) do { __builtin_amdgcn_s_setprio(1); _Pragma("unroll") for (int m = 0; m < 4; ++m) _Pragma("unroll") for (int n = 0; n < 2; ++n) _Pragma("unroll") for (int k = 0; k < 2; ++k) \
;         acc[ai][bj][m][n] = __builtin_amdgcn_mfma_f32_16x16x32_bf16(Bt[n][k], At[m][k], acc[ai][bj][m][n], 0, 0, 0); __builtin_amdgcn_s_setprio(0); } while (0)
; #define PG8_WAIT_V(n) asm volatile("s_waitcnt vmcnt(" #n ")" ::: "memory")
; #define PG8_WAIT_L(n) asm volatile("s_waitcnt lgkmcnt(" #n ")" ::: "memory")
; #define PG8_BAR __builtin_amdgcn_s_barrier()
; #define PG8_SCHED __builtin_amdgcn_sched_barrier(0)
; template <class Epi, class Sched, bool ALIGN_EPI = false, bool SP2 = false>
; __device__ __forceinline__ void gemm_phase(PG8_LAS unsigned char* lds, const Gemm g, const Sched& S, const Epi& E) {
;     ...
;             PG8_LDB(B0, 1, 0); PG8_LDB(B1, 1, 1); PG8_SCHED; PG8_LDA(At, 1, 0); PG8_STAGE(PG8_SA(0, 1), a2 + hstep, voffA);
;             PG8_WAIT_V(8); PG8_WAIT_L(0); PG8_BAR; PG8_MMA(0, 0, At, B0); PG8_MMA(0, 1, At, B1); PG8_BAR; PG8_SCHED;
;             PG8_LDA(At, 1, 1); PG8_STAGE(PG8_SB(1, 0), b3, voffB); PG8_STAGE(PG8_SB(1, 1), b3 + hstep, voffB); PG8_STAGE(PG8_SA(1, 0), a3, voffA);
;             PG8_WAIT_V(8); PG8_WAIT_L(0); PG8_BAR; PG8_MMA(1, 0, At, B0); PG8_MMA(1, 1, At, B1); PG8_BAR; PG8_SCHED;
	v_mfma_f32_16x16x32_bf16 v[40:43], v[198:201], v[238:241], v[40:43]
	s_setprio 0
	s_add_i32 s16, s18, s44
	v_lshl_add_u64 v[2:3], v[2:3], 0, s[20:21]
	s_mov_b32 m0, s16
	ds_read_b128 v[210:213], v196 offset:49152
	ds_read_b128 v[214:217], v196 offset:50176
	ds_read_b128 v[218:221], v196 offset:51200
	ds_read_b128 v[222:225], v196 offset:52224
	ds_read_b128 v[226:229], v196 offset:53248
	ds_read_b128 v[230:233], v196 offset:54272
	ds_read_b128 v[234:237], v196 offset:55296
	ds_read_b128 v[238:241], v196 offset:56320
	global_load_lds_dwordx4 v[2:3], off
	s_add_i32 m0, s16, 0x2000
	s_add_u32 s16, s40, 0x40080
	v_lshl_add_u64 v[2:3], v[156:157], 0, s[20:21]
	s_addc_u32 s17, s41, 0
	s_add_i32 s18, s33, s44
	global_load_lds_dwordx4 v[2:3], off
	v_lshl_add_u64 v[2:3], s[16:17], 0, v[162:163]
	s_mov_b32 m0, s18
	s_nop 0
	global_load_lds_dwordx4 v[2:3], off
	v_lshl_add_u64 v[2:3], s[16:17], 0, v[158:159]
	s_add_i32 m0, s18, 0x2000
	s_nop 0
	global_load_lds_dwordx4 v[2:3], off
	v_lshl_add_u64 v[2:3], v[242:243], 0, s[20:21]
	v_lshl_add_u64 v[244:245], v[244:245], 0, s[20:21]
	s_waitcnt vmcnt(6)
	s_waitcnt lgkmcnt(0)
	s_barrier
	s_setprio 1
	s_waitcnt lgkmcnt(0)
	v_mfma_f32_16x16x32_bf16 v[100:103], v[136:139], v[210:213], v[100:103]
	v_mfma_f32_16x16x32_bf16 v[96:99], v[144:147], v[210:213], v[96:99]
	v_mfma_f32_16x16x32_bf16 v[92:95], v[136:139], v[218:221], v[92:95]
	s_mov_b32 m0, s49
	v_mfma_f32_16x16x32_bf16 v[88:91], v[144:147], v[218:221], v[88:91]
	global_load_lds_dwordx4 v[2:3], off
	v_mfma_f32_16x16x32_bf16 v[80:83], v[136:139], v[226:229], v[80:83]
	v_mfma_f32_16x16x32_bf16 v[72:75], v[144:147], v[226:229], v[72:75]
	v_mfma_f32_16x16x32_bf16 v[60:63], v[136:139], v[234:237], v[60:63]
	v_mfma_f32_16x16x32_bf16 v[56:59], v[144:147], v[234:237], v[56:59]
	v_mfma_f32_16x16x32_bf16 v[100:103], v[140:143], v[214:217], v[100:103]
	v_mfma_f32_16x16x32_bf16 v[96:99], v[148:151], v[214:217], v[96:99]
	v_mfma_f32_16x16x32_bf16 v[92:95], v[140:143], v[222:225], v[92:95]
	s_mov_b32 m0, s50
	v_mfma_f32_16x16x32_bf16 v[88:91], v[148:151], v[222:225], v[88:91]
	global_load_lds_dwordx4 v[244:245], off
	v_mfma_f32_16x16x32_bf16 v[80:83], v[140:143], v[230:233], v[80:83]
	v_mfma_f32_16x16x32_bf16 v[72:75], v[148:151], v[230:233], v[72:75]
	v_mfma_f32_16x16x32_bf16 v[60:63], v[140:143], v[238:241], v[60:63]
	v_mfma_f32_16x16x32_bf16 v[56:59], v[148:151], v[238:241], v[56:59]
	s_setprio 0
	s_setprio 1
	v_mfma_f32_16x16x32_bf16 v[36:39], v[152:155], v[210:213], v[36:39]
	v_mfma_f32_16x16x32_bf16 v[32:35], v[190:193], v[210:213], v[32:35]
	v_mfma_f32_16x16x32_bf16 v[28:31], v[152:155], v[218:221], v[28:31]
	v_mfma_f32_16x16x32_bf16 v[24:27], v[190:193], v[218:221], v[24:27]
	v_mfma_f32_16x16x32_bf16 v[20:23], v[152:155], v[226:229], v[20:23]
	v_mfma_f32_16x16x32_bf16 v[16:19], v[190:193], v[226:229], v[16:19]
	v_mfma_f32_16x16x32_bf16 v[12:15], v[152:155], v[234:237], v[12:15]
	v_mfma_f32_16x16x32_bf16 v[8:11], v[190:193], v[234:237], v[8:11]
	v_mfma_f32_16x16x32_bf16 v[36:39], v[186:189], v[214:217], v[36:39]
	v_mfma_f32_16x16x32_bf16 v[32:35], v[198:201], v[214:217], v[32:35]
	v_mfma_f32_16x16x32_bf16 v[28:31], v[186:189], v[222:225], v[28:31]
	v_mfma_f32_16x16x32_bf16 v[24:27], v[198:201], v[222:225], v[24:27]
	v_mfma_f32_16x16x32_bf16 v[20:23], v[186:189], v[230:233], v[20:23]
	v_mfma_f32_16x16x32_bf16 v[16:19], v[198:201], v[230:233], v[16:19]
	v_mfma_f32_16x16x32_bf16 v[12:15], v[186:189], v[238:241], v[12:15]
	s_barrier
	v_mfma_f32_16x16x32_bf16 v[8:11], v[198:201], v[238:241], v[8:11]
	s_setprio 0
	s_add_i32 s55, s55, 2
	s_add_u32 s8, s8, 0x100
	s_addc_u32 s9, s9, 0
	s_add_u32 s53, s53, 0x100
	s_addc_u32 s54, s54, 0
	s_cmp_gt_u32 s55, 13
	s_cbranch_scc0 .LBB0_165
	s_and_b64 vcc, exec, s[10:11]
	s_cbranch_vccz .LBB0_168
	s_barrier
	s_setprio 1

; #define PG8_STAGE(bufoff, gbase, voff) do { _Pragma("unroll") for (int _i = 0; _i < 2; ++_i) \
;         __builtin_amdgcn_global_load_lds((const unsigned*)((const char*)(gbase) + (voff)[_i]), (PG8_LAS unsigned*)(lds + (bufoff) + ldsw + _i * 8192), 16, 0, 0); } while (0)
; #define PG8_LDA(dst, b, h) do { _Pragma("unroll") for (int m = 0; m < 4; ++m) _Pragma("unroll") for (int k = 0; k < 2; ++k) dst[m][k] = *(const PG8_LAS bf16x8*)(lds + PG8_SA(b, h) + aoff + m * 2048 + k * 1024); } while (0)
; #define PG8_LDB(dst, b, h) do { _Pragma("unroll") for (int n = 0; n < 2; ++n) _Pragma("unroll") for (int k = 0; k < 2; ++k) dst[n][k] = *(const PG8_LAS bf16x8*)(lds + PG8_SB(b, h) + boff + n * 2048 + k * 1024); } while (0)
; #define PG8_MMA(ai, bj, At, Bt) do { __builtin_amdgcn_s_setprio(1); _Pragma("unroll") for (int m = 0; m < 4; ++m) _Pragma("unroll") for (int n = 0; n < 2; ++n) _Pragma("unroll") for (int k = 0; k < 2; ++k) \
;         acc[ai][bj][m][n] = __builtin_amdgcn_mfma_f32_16x16x32_bf16(Bt[n][k], At[m][k], acc[ai][bj][m][n], 0, 0, 0); __builtin_amdgcn_s_setprio(0); } while (0)
; #define PG8_WAIT_V(n) asm volatile("s_waitcnt vmcnt(" #n ")" ::: "memory")
; #define PG8_BAR __builtin_amdgcn_s_barrier()
; template <class Epi, class Sched, bool ALIGN_EPI = false, bool SP2 = false>
; __device__ __forceinline__ void gemm_phase(PG8_LAS unsigned char* lds, const Gemm g, const Sched& S, const Epi& E) {
;     ...
;         for (int t = 0; t < nt; t += 2) {
;             const bool last = (t == nt - 2);
;             const char* a1 = cA + (size_t)(t + 1) * kstep;
;             const char* a2 = last ? nA : cA + (size_t)(t + 2) * kstep; const char* b2 = last ? nB : cB + (size_t)(t + 2) * kstep;
;             const char* a3 = a2 + kstep; const char* b3 = b2 + kstep;
;             if (last && has_next) S.a_ready(nxt);
;             if constexpr (SP2) {
;             PG8_LDB(B0, 0, 0); PG8_LDB(B1, 0, 1); PG8_SCHED; PG8_LDA(At, 0, 0); PG8_STAGE(PG8_SA(1, 1), a1 + hstep, voffA);
;             PG8_WAIT_V(8); PG8_WAIT_L(0); PG8_BAR; PG8_MMA(0, 0, At, B0); PG8_MMA(0, 1, At, B1); PG8_BAR; PG8_SCHED;
;             PG8_LDA(At, 0, 1); PG8_STAGE(PG8_SB(0, 0), b2, voffB); PG8_STAGE(PG8_SB(0, 1), b2 + hstep, voffB); PG8_STAGE(PG8_SA(0, 0), a2, voffA);
;             PG8_WAIT_V(8); PG8_WAIT_L(0); PG8_BAR; PG8_MMA(1, 0, At, B0); PG8_MMA(1, 1, At, B1); PG8_BAR; PG8_SCHED;
.LBB0_203:
	s_add_i32 s36, s28, 2
	s_add_u32 s16, s24, 0x80
	s_addc_u32 s17, s25, 0
	s_add_i32 s18, 0, 0x10000
	s_cmp_eq_u32 s60, s28
	s_cselect_b32 s29, s3, s17
	s_cselect_b32 s28, s2, s16
	v_add_u32_e32 v137, s18, v200
	s_cselect_b32 s17, s9, s35
	s_cselect_b32 s16, s8, s23
	s_add_i32 s19, 0, 0x14000
	ds_read_b128 v[144:147], v137
	ds_read_b128 v[148:151], v137 offset:1024
	ds_read_b128 v[152:155], v137 offset:2048
	ds_read_b128 v[156:159], v137 offset:3072
	v_add_u32_e32 v137, s19, v200
	ds_read_b128 v[160:163], v137
	ds_read_b128 v[178:181], v137 offset:1024
	ds_read_b128 v[182:185], v137 offset:2048
	ds_read_b128 v[186:189], v137 offset:3072
	v_lshl_add_u64 v[198:199], s[24:25], 0, v[140:141]
	s_add_i32 m0, s52, 0xc000
	ds_read_b128 v[190:193], v210
	ds_read_b128 v[194:197], v210 offset:1024
	ds_read_b128 v[212:215], v210 offset:2048
	ds_read_b128 v[216:219], v210 offset:3072
	ds_read_b128 v[220:223], v210 offset:4096
	ds_read_b128 v[224:227], v210 offset:5120
	ds_read_b128 v[228:231], v210 offset:6144
	ds_read_b128 v[232:235], v210 offset:7168
	global_load_lds_dwordx4 v[198:199], off
	v_lshl_add_u64 v[198:199], s[24:25], 0, v[142:143]
	s_add_i32 m0, s52, 0xe000
	s_nop 0
	global_load_lds_dwordx4 v[198:199], off
	s_waitcnt vmcnt(8)
	s_waitcnt lgkmcnt(0)
	s_barrier
	s_setprio 1
	s_waitcnt lgkmcnt(0)
	v_mfma_f32_16x16x32_bf16 v[132:135], v[144:147], v[190:193], v[132:135]
	v_mfma_f32_16x16x32_bf16 v[128:131], v[152:155], v[190:193], v[128:131]
	v_mfma_f32_16x16x32_bf16 v[116:119], v[144:147], v[212:215], v[116:119]
	v_mfma_f32_16x16x32_bf16 v[112:115], v[152:155], v[212:215], v[112:115]
	v_mfma_f32_16x16x32_bf16 v[100:103], v[144:147], v[220:223], v[100:103]
	v_mfma_f32_16x16x32_bf16 v[96:99], v[152:155], v[220:223], v[96:99]
	v_mfma_f32_16x16x32_bf16 v[84:87], v[144:147], v[228:231], v[84:87]
	v_mfma_f32_16x16x32_bf16 v[80:83], v[152:155], v[228:231], v[80:83]
	v_mfma_f32_16x16x32_bf16 v[132:135], v[148:151], v[194:197], v[132:135]
	v_mfma_f32_16x16x32_bf16 v[128:131], v[156:159], v[194:197], v[128:131]
	v_mfma_f32_16x16x32_bf16 v[116:119], v[148:151], v[216:219], v[116:119]
	v_mfma_f32_16x16x32_bf16 v[112:115], v[156:159], v[216:219], v[112:115]
	v_mfma_f32_16x16x32_bf16 v[100:103], v[148:151], v[224:227], v[100:103]
	v_mfma_f32_16x16x32_bf16 v[96:99], v[156:159], v[224:227], v[96:99]
	v_mfma_f32_16x16x32_bf16 v[84:87], v[148:151], v[232:235], v[84:87]
	v_mfma_f32_16x16x32_bf16 v[80:83], v[156:159], v[232:235], v[80:83]
	s_setprio 0
	s_setprio 1
	v_mfma_f32_16x16x32_bf16 v[124:127], v[160:163], v[190:193], v[124:127]
	v_mfma_f32_16x16x32_bf16 v[120:123], v[182:185], v[190:193], v[120:123]
	v_mfma_f32_16x16x32_bf16 v[108:111], v[160:163], v[212:215], v[108:111]
	v_mfma_f32_16x16x32_bf16 v[104:107], v[182:185], v[212:215], v[104:107]
	v_mfma_f32_16x16x32_bf16 v[92:95], v[160:163], v[220:223], v[92:95]
	v_mfma_f32_16x16x32_bf16 v[88:91], v[182:185], v[220:223], v[88:91]
	v_mfma_f32_16x16x32_bf16 v[76:79], v[160:163], v[228:231], v[76:79]
	v_mfma_f32_16x16x32_bf16 v[72:75], v[182:185], v[228:231], v[72:75]
	v_mfma_f32_16x16x32_bf16 v[124:127], v[178:181], v[194:197], v[124:127]
	v_mfma_f32_16x16x32_bf16 v[120:123], v[186:189], v[194:197], v[120:123]
	v_mfma_f32_16x16x32_bf16 v[108:111], v[178:181], v[216:219], v[108:111]
	v_mfma_f32_16x16x32_bf16 v[104:107], v[186:189], v[216:219], v[104:107]
	v_mfma_f32_16x16x32_bf16 v[92:95], v[178:181], v[224:227], v[92:95]
	v_mfma_f32_16x16x32_bf16 v[88:91], v[186:189], v[224:227], v[88:91]
	v_mfma_f32_16x16x32_bf16 v[76:79], v[178:181], v[232:235], v[76:79]
	s_barrier
	v_mfma_f32_16x16x32_bf16 v[72:75], v[186:189], v[232:235], v[72:75]
	s_setprio 0
	s_add_i32 s18, s18, s41
	v_lshl_add_u64 v[198:199], s[16:17], 0, v[0:1]
	s_mov_b32 m0, s18
	ds_read_b128 v[190:193], v210 offset:16384
	ds_read_b128 v[194:197], v210 offset:17408
	ds_read_b128 v[212:215], v210 offset:18432
	ds_read_b128 v[216:219], v210 offset:19456
	ds_read_b128 v[220:223], v210 offset:20480
	ds_read_b128 v[224:227], v210 offset:21504
	ds_read_b128 v[228:231], v210 offset:22528
	ds_read_b128 v[232:235], v210 offset:23552
	global_load_lds_dwordx4 v[198:199], off
	s_add_i32 m0, s18, 0x2000
	v_lshl_add_u64 v[236:237], s[16:17], 0, v[2:3]
	s_add_u32 s16, s16, s12
	s_addc_u32 s17, s17, 0
	s_add_i32 s18, s19, s41
	global_load_lds_dwordx4 v[236:237], off
	v_lshl_add_u64 v[238:239], s[16:17], 0, v[0:1]
	s_mov_b32 m0, s18
	v_lshl_add_u64 v[240:241], s[16:17], 0, v[2:3]
	global_load_lds_dwordx4 v[238:239], off
	s_add_i32 m0, s18, 0x2000
	v_lshl_add_u64 v[242:243], s[28:29], 0, v[0:1]
	global_load_lds_dwordx4 v[240:241], off
	v_lshl_add_u64 v[244:245], s[28:29], 0, v[2:3]
	s_waitcnt vmcnt(6)
	s_waitcnt lgkmcnt(0)
	s_barrier
; #define PG8_STAGE(bufoff, gbase, voff) do { _Pragma("unroll") for (int _i = 0; _i < 2; ++_i) \
;         __builtin_amdgcn_global_load_lds((const unsigned*)((const char*)(gbase) + (voff)[_i]), (PG8_LAS unsigned*)(lds + (bufoff) + ldsw + _i * 8192), 16, 0, 0); } while (0)
; #define PG8_LDA(dst, b, h) do { _Pragma("unroll") for (int m = 0; m < 4; ++m) _Pragma("unroll") for (int k = 0; k < 2; ++k) dst[m][k] = *(const PG8_LAS bf16x8*)(lds + PG8_SA(b, h) + aoff + m * 2048 + k * 1024); } while (0)
; #define PG8_LDB(dst, b, h) do { _Pragma("unroll") for (int n = 0; n < 2; ++n) _Pragma("unroll") for (int k = 0; k < 2; ++k) dst[n][k] = *(const PG8_LAS bf16x8*)(lds + PG8_SB(b, h) + boff + n * 2048 + k * 1024); } while (0)
; #define PG8_MMA(ai, bj, At, Bt) do { __builtin_amdgcn_s_setprio(1); _Pragma("unroll") for (int m = 0; m < 4; ++m) _Pragma("unroll") for (int n = 0; n < 2; ++n) _Pragma("unroll") for (int k = 0; k < 2; ++k) \
;         acc[ai][bj][m][n] = __builtin_amdgcn_mfma_f32_16x16x32_bf16(Bt[n][k], At[m][k], acc[ai][bj][m][n], 0, 0, 0); __builtin_amdgcn_s_setprio(0); } while (0)
; #define PG8_WAIT_V(n) asm volatile("s_waitcnt vmcnt(" #n ")" ::: "memory")
; #define PG8_WAIT_L(n) asm volatile("s_waitcnt lgkmcnt(" #n ")" ::: "memory")
; #define PG8_BAR __builtin_amdgcn_s_barrier()
; #define PG8_SCHED __builtin_amdgcn_sched_barrier(0)
; template <class Epi, class Sched, bool ALIGN_EPI = false, bool SP2 = false>
; __device__ __forceinline__ void gemm_phase(PG8_LAS unsigned char* lds, const Gemm g, const Sched& S, const Epi& E) {
;     ...
;             PG8_WAIT_V(8); PG8_WAIT_L(0); PG8_BAR; PG8_MMA(0, 0, At, B0); PG8_MMA(0, 1, At, B1); PG8_BAR; PG8_SCHED;
;             PG8_LDA(At, 0, 1); PG8_STAGE(PG8_SB(0, 0), b2, voffB); PG8_STAGE(PG8_SB(0, 1), b2 + hstep, voffB); PG8_STAGE(PG8_SA(0, 0), a2, voffA);
;             PG8_WAIT_V(8); PG8_WAIT_L(0); PG8_BAR; PG8_MMA(1, 0, At, B0); PG8_MMA(1, 1, At, B1); PG8_BAR; PG8_SCHED;
;             PG8_LDB(B0, 1, 0); PG8_LDB(B1, 1, 1); PG8_SCHED; PG8_LDA(At, 1, 0); PG8_STAGE(PG8_SA(0, 1), a2 + hstep, voffA);
;             PG8_WAIT_V(8); PG8_WAIT_L(0); PG8_BAR; PG8_MMA(0, 0, At, B0); PG8_MMA(0, 1, At, B1); PG8_BAR; PG8_SCHED;
	s_setprio 1
	s_waitcnt lgkmcnt(0)
	v_mfma_f32_16x16x32_bf16 v[68:71], v[144:147], v[190:193], v[68:71]
	v_mfma_f32_16x16x32_bf16 v[64:67], v[152:155], v[190:193], v[64:67]
	v_mfma_f32_16x16x32_bf16 v[52:55], v[144:147], v[212:215], v[52:55]
	s_mov_b32 m0, s52
	v_mfma_f32_16x16x32_bf16 v[48:51], v[152:155], v[212:215], v[48:51]
	global_load_lds_dwordx4 v[242:243], off
	v_mfma_f32_16x16x32_bf16 v[36:39], v[144:147], v[220:223], v[36:39]
	v_mfma_f32_16x16x32_bf16 v[32:35], v[152:155], v[220:223], v[32:35]
	v_mfma_f32_16x16x32_bf16 v[20:23], v[144:147], v[228:231], v[20:23]
	v_mfma_f32_16x16x32_bf16 v[16:19], v[152:155], v[228:231], v[16:19]
	v_mfma_f32_16x16x32_bf16 v[68:71], v[148:151], v[194:197], v[68:71]
	v_mfma_f32_16x16x32_bf16 v[64:67], v[156:159], v[194:197], v[64:67]
	v_mfma_f32_16x16x32_bf16 v[52:55], v[148:151], v[216:219], v[52:55]
	s_mov_b32 m0, s53
	v_mfma_f32_16x16x32_bf16 v[48:51], v[156:159], v[216:219], v[48:51]
	global_load_lds_dwordx4 v[244:245], off
	v_mfma_f32_16x16x32_bf16 v[36:39], v[148:151], v[224:227], v[36:39]
	v_mfma_f32_16x16x32_bf16 v[32:35], v[156:159], v[224:227], v[32:35]
	v_mfma_f32_16x16x32_bf16 v[20:23], v[148:151], v[232:235], v[20:23]
	v_mfma_f32_16x16x32_bf16 v[16:19], v[156:159], v[232:235], v[16:19]
	s_setprio 0
	s_setprio 1
	v_mfma_f32_16x16x32_bf16 v[60:63], v[160:163], v[190:193], v[60:63]
	v_mfma_f32_16x16x32_bf16 v[56:59], v[182:185], v[190:193], v[56:59]
	v_mfma_f32_16x16x32_bf16 v[44:47], v[160:163], v[212:215], v[44:47]
	v_mfma_f32_16x16x32_bf16 v[40:43], v[182:185], v[212:215], v[40:43]
	v_mfma_f32_16x16x32_bf16 v[28:31], v[160:163], v[220:223], v[28:31]
	v_mfma_f32_16x16x32_bf16 v[24:27], v[182:185], v[220:223], v[24:27]
	v_mfma_f32_16x16x32_bf16 v[12:15], v[160:163], v[228:231], v[12:15]
	v_mfma_f32_16x16x32_bf16 v[8:11], v[182:185], v[228:231], v[8:11]
	v_mfma_f32_16x16x32_bf16 v[60:63], v[178:181], v[194:197], v[60:63]
	v_mfma_f32_16x16x32_bf16 v[56:59], v[186:189], v[194:197], v[56:59]
	v_mfma_f32_16x16x32_bf16 v[44:47], v[178:181], v[216:219], v[44:47]
	v_mfma_f32_16x16x32_bf16 v[40:43], v[186:189], v[216:219], v[40:43]
	v_mfma_f32_16x16x32_bf16 v[28:31], v[178:181], v[224:227], v[28:31]
	v_mfma_f32_16x16x32_bf16 v[24:27], v[186:189], v[224:227], v[24:27]
	v_mfma_f32_16x16x32_bf16 v[12:15], v[178:181], v[232:235], v[12:15]
	s_barrier
	v_mfma_f32_16x16x32_bf16 v[8:11], v[186:189], v[232:235], v[8:11]
	s_setprio 0
	s_add_i32 s18, 0, 0x18000
	v_add_u32_e32 v137, s18, v200
	ds_read_b128 v[144:147], v137
	ds_read_b128 v[148:151], v137 offset:1024
	ds_read_b128 v[152:155], v137 offset:2048
	ds_read_b128 v[156:159], v137 offset:3072
	v_add_u32_e32 v137, s33, v200
	ds_read_b128 v[160:163], v137
	ds_read_b128 v[178:181], v137 offset:1024
	ds_read_b128 v[182:185], v137 offset:2048
	ds_read_b128 v[186:189], v137 offset:3072
	s_add_u32 s16, s28, s12
	s_addc_u32 s17, s29, 0
	s_mov_b32 m0, s54
	v_lshl_add_u64 v[246:247], s[16:17], 0, v[0:1]
	ds_read_b128 v[190:193], v210 offset:32768
	ds_read_b128 v[194:197], v210 offset:33792
	ds_read_b128 v[212:215], v210 offset:34816
	ds_read_b128 v[216:219], v210 offset:35840
	ds_read_b128 v[220:223], v210 offset:36864
	ds_read_b128 v[224:227], v210 offset:37888
	ds_read_b128 v[228:231], v210 offset:38912
	ds_read_b128 v[232:235], v210 offset:39936
	global_load_lds_dwordx4 v[246:247], off
	v_lshl_add_u64 v[246:247], s[16:17], 0, v[2:3]
	s_mov_b32 m0, s55
	s_nop 0
	global_load_lds_dwordx4 v[246:247], off
	s_waitcnt vmcnt(8)
	s_waitcnt lgkmcnt(0)
	s_barrier
	s_setprio 1
	s_waitcnt lgkmcnt(0)
	v_mfma_f32_16x16x32_bf16 v[132:135], v[144:147], v[190:193], v[132:135]
	v_mfma_f32_16x16x32_bf16 v[128:131], v[152:155], v[190:193], v[128:131]
	v_mfma_f32_16x16x32_bf16 v[116:119], v[144:147], v[212:215], v[116:119]
	v_mfma_f32_16x16x32_bf16 v[112:115], v[152:155], v[212:215], v[112:115]
	v_mfma_f32_16x16x32_bf16 v[100:103], v[144:147], v[220:223], v[100:103]
	v_mfma_f32_16x16x32_bf16 v[96:99], v[152:155], v[220:223], v[96:99]
	v_mfma_f32_16x16x32_bf16 v[84:87], v[144:147], v[228:231], v[84:87]
	v_mfma_f32_16x16x32_bf16 v[80:83], v[152:155], v[228:231], v[80:83]
	v_mfma_f32_16x16x32_bf16 v[132:135], v[148:151], v[194:197], v[132:135]
	v_mfma_f32_16x16x32_bf16 v[128:131], v[156:159], v[194:197], v[128:131]
	v_mfma_f32_16x16x32_bf16 v[116:119], v[148:151], v[216:219], v[116:119]
	v_mfma_f32_16x16x32_bf16 v[112:115], v[156:159], v[216:219], v[112:115]
	v_mfma_f32_16x16x32_bf16 v[100:103], v[148:151], v[224:227], v[100:103]
	v_mfma_f32_16x16x32_bf16 v[96:99], v[156:159], v[224:227], v[96:99]
	v_mfma_f32_16x16x32_bf16 v[84:87], v[148:151], v[232:235], v[84:87]
	v_mfma_f32_16x16x32_bf16 v[80:83], v[156:159], v[232:235], v[80:83]
	s_setprio 0
	s_setprio 1
	v_mfma_f32_16x16x32_bf16 v[124:127], v[160:163], v[190:193], v[124:127]
	v_mfma_f32_16x16x32_bf16 v[120:123], v[182:185], v[190:193], v[120:123]
	v_mfma_f32_16x16x32_bf16 v[108:111], v[160:163], v[212:215], v[108:111]
	v_mfma_f32_16x16x32_bf16 v[104:107], v[182:185], v[212:215], v[104:107]
	v_mfma_f32_16x16x32_bf16 v[92:95], v[160:163], v[220:223], v[92:95]
	v_mfma_f32_16x16x32_bf16 v[88:91], v[182:185], v[220:223], v[88:91]
	v_mfma_f32_16x16x32_bf16 v[76:79], v[160:163], v[228:231], v[76:79]
	v_mfma_f32_16x16x32_bf16 v[72:75], v[182:185], v[228:231], v[72:75]
	v_mfma_f32_16x16x32_bf16 v[124:127], v[178:181], v[194:197], v[124:127]
	v_mfma_f32_16x16x32_bf16 v[120:123], v[186:189], v[194:197], v[120:123]
	v_mfma_f32_16x16x32_bf16 v[108:111], v[178:181], v[216:219], v[108:111]
	v_mfma_f32_16x16x32_bf16 v[104:107], v[186:189], v[216:219], v[104:107]
	v_mfma_f32_16x16x32_bf16 v[92:95], v[178:181], v[224:227], v[92:95]
	v_mfma_f32_16x16x32_bf16 v[88:91], v[186:189], v[224:227], v[88:91]
	v_mfma_f32_16x16x32_bf16 v[76:79], v[178:181], v[232:235], v[76:79]
	s_barrier
; #define PG8_STAGE(bufoff, gbase, voff) do { _Pragma("unroll") for (int _i = 0; _i < 2; ++_i) \
;         __builtin_amdgcn_global_load_lds((const unsigned*)((const char*)(gbase) + (voff)[_i]), (PG8_LAS unsigned*)(lds + (bufoff) + ldsw + _i * 8192), 16, 0, 0); } while (0)
; #define PG8_LDA(dst, b, h) do { _Pragma("unroll") for (int m = 0; m < 4; ++m) _Pragma("unroll") for (int k = 0; k < 2; ++k) dst[m][k] = *(const PG8_LAS bf16x8*)(lds + PG8_SA(b, h) + aoff + m * 2048 + k * 1024); } while (0)
; #define PG8_LDB(dst, b, h) do { _Pragma("unroll") for (int n = 0; n < 2; ++n) _Pragma("unroll") for (int k = 0; k < 2; ++k) dst[n][k] = *(const PG8_LAS bf16x8*)(lds + PG8_SB(b, h) + boff + n * 2048 + k * 1024); } while (0)
; #define PG8_MMA(ai, bj, At, Bt) do { __builtin_amdgcn_s_setprio(1); _Pragma("unroll") for (int m = 0; m < 4; ++m) _Pragma("unroll") for (int n = 0; n < 2; ++n) _Pragma("unroll") for (int k = 0; k < 2; ++k) \
;         acc[ai][bj][m][n] = __builtin_amdgcn_mfma_f32_16x16x32_bf16(Bt[n][k], At[m][k], acc[ai][bj][m][n], 0, 0, 0); __builtin_amdgcn_s_setprio(0); } while (0)
; #define PG8_WAIT_V(n) asm volatile("s_waitcnt vmcnt(" #n ")" ::: "memory")
; #define PG8_WAIT_L(n) asm volatile("s_waitcnt lgkmcnt(" #n ")" ::: "memory")
; #define PG8_BAR __builtin_amdgcn_s_barrier()
; #define PG8_SCHED __builtin_amdgcn_sched_barrier(0)
; template <class Epi, class Sched, bool ALIGN_EPI = false, bool SP2 = false>
; __device__ __forceinline__ void gemm_phase(PG8_LAS unsigned char* lds, const Gemm g, const Sched& S, const Epi& E) {
;     ...
;             PG8_LDB(B0, 1, 0); PG8_LDB(B1, 1, 1); PG8_SCHED; PG8_LDA(At, 1, 0); PG8_STAGE(PG8_SA(0, 1), a2 + hstep, voffA);
;             PG8_WAIT_V(8); PG8_WAIT_L(0); PG8_BAR; PG8_MMA(0, 0, At, B0); PG8_MMA(0, 1, At, B1); PG8_BAR; PG8_SCHED;
;             PG8_LDA(At, 1, 1); PG8_STAGE(PG8_SB(1, 0), b3, voffB); PG8_STAGE(PG8_SB(1, 1), b3 + hstep, voffB); PG8_STAGE(PG8_SA(1, 0), a3, voffA);
;             PG8_WAIT_V(8); PG8_WAIT_L(0); PG8_BAR; PG8_MMA(1, 0, At, B0); PG8_MMA(1, 1, At, B1); PG8_BAR; PG8_SCHED;
	v_mfma_f32_16x16x32_bf16 v[72:75], v[186:189], v[232:235], v[72:75]
	s_setprio 0
	s_add_i32 s16, s18, s41
	v_lshl_add_u64 v[198:199], v[198:199], 0, s[20:21]
	s_mov_b32 m0, s16
	ds_read_b128 v[190:193], v210 offset:49152
	ds_read_b128 v[194:197], v210 offset:50176
	ds_read_b128 v[212:215], v210 offset:51200
	ds_read_b128 v[216:219], v210 offset:52224
	ds_read_b128 v[220:223], v210 offset:53248
	ds_read_b128 v[224:227], v210 offset:54272
	ds_read_b128 v[228:231], v210 offset:55296
	ds_read_b128 v[232:235], v210 offset:56320
	global_load_lds_dwordx4 v[198:199], off
	v_lshl_add_u64 v[198:199], v[236:237], 0, s[20:21]
	s_add_i32 m0, s16, 0x2000
	s_add_i32 s16, s33, s41
	global_load_lds_dwordx4 v[198:199], off
	v_lshl_add_u64 v[198:199], v[238:239], 0, s[20:21]
	s_mov_b32 m0, s16
	s_nop 0
	global_load_lds_dwordx4 v[198:199], off
	v_lshl_add_u64 v[198:199], v[240:241], 0, s[20:21]
	s_add_i32 m0, s16, 0x2000
	s_nop 0
	global_load_lds_dwordx4 v[198:199], off
	v_lshl_add_u64 v[198:199], v[242:243], 0, s[20:21]
	v_lshl_add_u64 v[244:245], v[244:245], 0, s[20:21]
	s_waitcnt vmcnt(6)
	s_waitcnt lgkmcnt(0)
	s_barrier
	s_setprio 1
	s_waitcnt lgkmcnt(0)
	v_mfma_f32_16x16x32_bf16 v[68:71], v[144:147], v[190:193], v[68:71]
	v_mfma_f32_16x16x32_bf16 v[64:67], v[152:155], v[190:193], v[64:67]
	v_mfma_f32_16x16x32_bf16 v[52:55], v[144:147], v[212:215], v[52:55]
	s_mov_b32 m0, s56
	v_mfma_f32_16x16x32_bf16 v[48:51], v[152:155], v[212:215], v[48:51]
	global_load_lds_dwordx4 v[198:199], off
	v_mfma_f32_16x16x32_bf16 v[36:39], v[144:147], v[220:223], v[36:39]
	v_mfma_f32_16x16x32_bf16 v[32:35], v[152:155], v[220:223], v[32:35]
	v_mfma_f32_16x16x32_bf16 v[20:23], v[144:147], v[228:231], v[20:23]
	v_mfma_f32_16x16x32_bf16 v[16:19], v[152:155], v[228:231], v[16:19]
	v_mfma_f32_16x16x32_bf16 v[68:71], v[148:151], v[194:197], v[68:71]
	v_mfma_f32_16x16x32_bf16 v[64:67], v[156:159], v[194:197], v[64:67]
	v_mfma_f32_16x16x32_bf16 v[52:55], v[148:151], v[216:219], v[52:55]
	s_mov_b32 m0, s57
	v_mfma_f32_16x16x32_bf16 v[48:51], v[156:159], v[216:219], v[48:51]
	global_load_lds_dwordx4 v[244:245], off
	v_mfma_f32_16x16x32_bf16 v[36:39], v[148:151], v[224:227], v[36:39]
	v_mfma_f32_16x16x32_bf16 v[32:35], v[156:159], v[224:227], v[32:35]
	v_mfma_f32_16x16x32_bf16 v[20:23], v[148:151], v[232:235], v[20:23]
	v_mfma_f32_16x16x32_bf16 v[16:19], v[156:159], v[232:235], v[16:19]
	s_setprio 0
	s_setprio 1
	v_mfma_f32_16x16x32_bf16 v[60:63], v[160:163], v[190:193], v[60:63]
	v_mfma_f32_16x16x32_bf16 v[56:59], v[182:185], v[190:193], v[56:59]
	v_mfma_f32_16x16x32_bf16 v[44:47], v[160:163], v[212:215], v[44:47]
	v_mfma_f32_16x16x32_bf16 v[40:43], v[182:185], v[212:215], v[40:43]
	v_mfma_f32_16x16x32_bf16 v[28:31], v[160:163], v[220:223], v[28:31]
	v_mfma_f32_16x16x32_bf16 v[24:27], v[182:185], v[220:223], v[24:27]
	v_mfma_f32_16x16x32_bf16 v[12:15], v[160:163], v[228:231], v[12:15]
	v_mfma_f32_16x16x32_bf16 v[8:11], v[182:185], v[228:231], v[8:11]
	v_mfma_f32_16x16x32_bf16 v[60:63], v[178:181], v[194:197], v[60:63]
	v_mfma_f32_16x16x32_bf16 v[56:59], v[186:189], v[194:197], v[56:59]
	v_mfma_f32_16x16x32_bf16 v[44:47], v[178:181], v[216:219], v[44:47]
	v_mfma_f32_16x16x32_bf16 v[40:43], v[186:189], v[216:219], v[40:43]
	v_mfma_f32_16x16x32_bf16 v[28:31], v[178:181], v[224:227], v[28:31]
	v_mfma_f32_16x16x32_bf16 v[24:27], v[186:189], v[224:227], v[24:27]
	v_mfma_f32_16x16x32_bf16 v[12:15], v[178:181], v[232:235], v[12:15]
	s_barrier
	v_mfma_f32_16x16x32_bf16 v[8:11], v[186:189], v[232:235], v[8:11]
	s_setprio 0
	s_add_u32 s24, s24, 0x100
	s_addc_u32 s25, s25, 0
	s_add_u32 s23, s23, 0x100
	s_addc_u32 s35, s35, 0
	s_cmp_ge_u32 s36, s59
	s_mov_b32 s28, s36
	s_cbranch_scc0 .LBB0_203
	s_and_b64 vcc, exec, s[46:47]
	s_cbranch_vccz .LBB0_206
	s_barrier
	s_setprio 1

; #define PG8_STAGE(bufoff, gbase, voff) do { _Pragma("unroll") for (int _i = 0; _i < 2; ++_i) \
;         __builtin_amdgcn_global_load_lds((const unsigned*)((const char*)(gbase) + (voff)[_i]), (PG8_LAS unsigned*)(lds + (bufoff) + ldsw + _i * 8192), 16, 0, 0); } while (0)
; #define PG8_LDA(dst, b, h) do { _Pragma("unroll") for (int m = 0; m < 4; ++m) _Pragma("unroll") for (int k = 0; k < 2; ++k) dst[m][k] = *(const PG8_LAS bf16x8*)(lds + PG8_SA(b, h) + aoff + m * 2048 + k * 1024); } while (0)
; #define PG8_LDB(dst, b, h) do { _Pragma("unroll") for (int n = 0; n < 2; ++n) _Pragma("unroll") for (int k = 0; k < 2; ++k) dst[n][k] = *(const PG8_LAS bf16x8*)(lds + PG8_SB(b, h) + boff + n * 2048 + k * 1024); } while (0)
; #define PG8_MMA(ai, bj, At, Bt) do { __builtin_amdgcn_s_setprio(1); _Pragma("unroll") for (int m = 0; m < 4; ++m) _Pragma("unroll") for (int n = 0; n < 2; ++n) _Pragma("unroll") for (int k = 0; k < 2; ++k) \
;         acc[ai][bj][m][n] = __builtin_amdgcn_mfma_f32_16x16x32_bf16(Bt[n][k], At[m][k], acc[ai][bj][m][n], 0, 0, 0); __builtin_amdgcn_s_setprio(0); } while (0)
; #define PG8_WAIT_V(n) asm volatile("s_waitcnt vmcnt(" #n ")" ::: "memory")
; #define PG8_BAR __builtin_amdgcn_s_barrier()
; template <class Epi, class Sched, bool ALIGN_EPI = false, bool SP2 = false>
; __device__ __forceinline__ void gemm_phase(PG8_LAS unsigned char* lds, const Gemm g, const Sched& S, const Epi& E) {
;     ...
;         for (int t = 0; t < nt; t += 2) {
;             const bool last = (t == nt - 2);
;             const char* a1 = cA + (size_t)(t + 1) * kstep;
;             const char* a2 = last ? nA : cA + (size_t)(t + 2) * kstep; const char* b2 = last ? nB : cB + (size_t)(t + 2) * kstep;
;             const char* a3 = a2 + kstep; const char* b3 = b2 + kstep;
;             if (last && has_next) S.a_ready(nxt);
;             if constexpr (SP2) {
;             PG8_LDB(B0, 0, 0); PG8_LDB(B1, 0, 1); PG8_SCHED; PG8_LDA(At, 0, 0); PG8_STAGE(PG8_SA(1, 1), a1 + hstep, voffA);
;             PG8_WAIT_V(8); PG8_WAIT_L(0); PG8_BAR; PG8_MMA(0, 0, At, B0); PG8_MMA(0, 1, At, B1); PG8_BAR; PG8_SCHED;
;             PG8_LDA(At, 0, 1); PG8_STAGE(PG8_SB(0, 0), b2, voffB); PG8_STAGE(PG8_SB(0, 1), b2 + hstep, voffB); PG8_STAGE(PG8_SA(0, 0), a2, voffA);
;             PG8_WAIT_V(8); PG8_WAIT_L(0); PG8_BAR; PG8_MMA(1, 0, At, B0); PG8_MMA(1, 1, At, B1); PG8_BAR; PG8_SCHED;
.LBB0_257:
	s_add_u32 s16, s8, 0xfffc0080
	s_addc_u32 s17, s9, -1
	s_add_i32 s18, 0, 0x10000
	s_cmp_eq_u32 s55, 12
	s_cselect_b32 s43, s14, s17
	s_cselect_b32 s42, s15, s16
	v_add_u32_e32 v0, s18, v210
	s_cselect_b32 s41, s13, s54
	s_cselect_b32 s40, s25, s53
	s_add_i32 s19, 0, 0x14000
	ds_read_b128 v[104:107], v0
	ds_read_b128 v[140:143], v0 offset:1024
	ds_read_b128 v[144:147], v0 offset:2048
	ds_read_b128 v[148:151], v0 offset:3072
	v_add_u32_e32 v0, s19, v210
	ds_read_b128 v[152:155], v0
	ds_read_b128 v[156:159], v0 offset:1024
	ds_read_b128 v[160:163], v0 offset:2048
	ds_read_b128 v[192:195], v0 offset:3072
	v_lshl_add_u64 v[2:3], s[8:9], 0, v[188:189]
	s_add_i32 m0, s44, 0xc000
	ds_read_b128 v[196:199], v212
	ds_read_b128 v[214:217], v212 offset:1024
	ds_read_b128 v[218:221], v212 offset:2048
	ds_read_b128 v[222:225], v212 offset:3072
	ds_read_b128 v[226:229], v212 offset:4096
	ds_read_b128 v[230:233], v212 offset:5120
	ds_read_b128 v[234:237], v212 offset:6144
	ds_read_b128 v[238:241], v212 offset:7168
	global_load_lds_dwordx4 v[2:3], off
	v_lshl_add_u64 v[2:3], s[8:9], 0, v[190:191]
	s_add_i32 m0, s44, 0xe000
	s_nop 0
	global_load_lds_dwordx4 v[2:3], off
	s_waitcnt vmcnt(8)
	s_waitcnt lgkmcnt(0)
	s_barrier
	s_setprio 1
	s_waitcnt lgkmcnt(0)
	v_mfma_f32_16x16x32_bf16 v[136:139], v[104:107], v[196:199], v[136:139]
	v_mfma_f32_16x16x32_bf16 v[128:131], v[144:147], v[196:199], v[128:131]
	v_mfma_f32_16x16x32_bf16 v[120:123], v[104:107], v[218:221], v[120:123]
	v_mfma_f32_16x16x32_bf16 v[112:115], v[144:147], v[218:221], v[112:115]
	v_mfma_f32_16x16x32_bf16 v[100:103], v[104:107], v[226:229], v[100:103]
	v_mfma_f32_16x16x32_bf16 v[92:95], v[144:147], v[226:229], v[92:95]
	v_mfma_f32_16x16x32_bf16 v[84:87], v[104:107], v[234:237], v[84:87]
	v_mfma_f32_16x16x32_bf16 v[76:79], v[144:147], v[234:237], v[76:79]
	v_mfma_f32_16x16x32_bf16 v[136:139], v[140:143], v[214:217], v[136:139]
	v_mfma_f32_16x16x32_bf16 v[128:131], v[148:151], v[214:217], v[128:131]
	v_mfma_f32_16x16x32_bf16 v[120:123], v[140:143], v[222:225], v[120:123]
	v_mfma_f32_16x16x32_bf16 v[112:115], v[148:151], v[222:225], v[112:115]
	v_mfma_f32_16x16x32_bf16 v[100:103], v[140:143], v[230:233], v[100:103]
	v_mfma_f32_16x16x32_bf16 v[92:95], v[148:151], v[230:233], v[92:95]
	v_mfma_f32_16x16x32_bf16 v[84:87], v[140:143], v[238:241], v[84:87]
	v_mfma_f32_16x16x32_bf16 v[76:79], v[148:151], v[238:241], v[76:79]
	s_setprio 0
	s_setprio 1
	v_mfma_f32_16x16x32_bf16 v[132:135], v[152:155], v[196:199], v[132:135]
	v_mfma_f32_16x16x32_bf16 v[124:127], v[160:163], v[196:199], v[124:127]
	v_mfma_f32_16x16x32_bf16 v[116:119], v[152:155], v[218:221], v[116:119]
	v_mfma_f32_16x16x32_bf16 v[108:111], v[160:163], v[218:221], v[108:111]
	v_mfma_f32_16x16x32_bf16 v[96:99], v[152:155], v[226:229], v[96:99]
	v_mfma_f32_16x16x32_bf16 v[88:91], v[160:163], v[226:229], v[88:91]
	v_mfma_f32_16x16x32_bf16 v[80:83], v[152:155], v[234:237], v[80:83]
	v_mfma_f32_16x16x32_bf16 v[72:75], v[160:163], v[234:237], v[72:75]
	v_mfma_f32_16x16x32_bf16 v[132:135], v[156:159], v[214:217], v[132:135]
	v_mfma_f32_16x16x32_bf16 v[124:127], v[192:195], v[214:217], v[124:127]
	v_mfma_f32_16x16x32_bf16 v[116:119], v[156:159], v[222:225], v[116:119]
	v_mfma_f32_16x16x32_bf16 v[108:111], v[192:195], v[222:225], v[108:111]
	v_mfma_f32_16x16x32_bf16 v[96:99], v[156:159], v[230:233], v[96:99]
	v_mfma_f32_16x16x32_bf16 v[88:91], v[192:195], v[230:233], v[88:91]
	v_mfma_f32_16x16x32_bf16 v[80:83], v[156:159], v[238:241], v[80:83]
	s_barrier
	v_mfma_f32_16x16x32_bf16 v[72:75], v[192:195], v[238:241], v[72:75]
	s_setprio 0
	s_add_i32 s16, s18, s36
	v_lshl_add_u64 v[2:3], s[40:41], 0, v[182:183]
	s_mov_b32 m0, s16
	ds_read_b128 v[196:199], v212 offset:16384
	ds_read_b128 v[214:217], v212 offset:17408
	ds_read_b128 v[218:221], v212 offset:18432
	ds_read_b128 v[222:225], v212 offset:19456
	ds_read_b128 v[226:229], v212 offset:20480
	ds_read_b128 v[230:233], v212 offset:21504
	ds_read_b128 v[234:237], v212 offset:22528
	ds_read_b128 v[238:241], v212 offset:23552
	global_load_lds_dwordx4 v[2:3], off
	s_add_i32 m0, s16, 0x2000
	s_add_u32 s16, s40, 0x40000
	v_lshl_add_u64 v[200:201], s[40:41], 0, v[178:179]
	s_addc_u32 s17, s41, 0
	s_add_i32 s18, s19, s36
	global_load_lds_dwordx4 v[200:201], off
	v_lshl_add_u64 v[242:243], s[16:17], 0, v[182:183]
	s_mov_b32 m0, s18
	v_lshl_add_u64 v[244:245], s[42:43], 0, v[180:181]
	global_load_lds_dwordx4 v[242:243], off
	v_lshl_add_u64 v[242:243], s[16:17], 0, v[178:179]
	s_add_i32 m0, s18, 0x2000
	s_nop 0
	global_load_lds_dwordx4 v[242:243], off
	v_lshl_add_u64 v[242:243], s[42:43], 0, v[184:185]
	s_waitcnt vmcnt(6)
	s_waitcnt lgkmcnt(0)
	s_barrier
; #define PG8_STAGE(bufoff, gbase, voff) do { _Pragma("unroll") for (int _i = 0; _i < 2; ++_i) \
;         __builtin_amdgcn_global_load_lds((const unsigned*)((const char*)(gbase) + (voff)[_i]), (PG8_LAS unsigned*)(lds + (bufoff) + ldsw + _i * 8192), 16, 0, 0); } while (0)
; #define PG8_LDA(dst, b, h) do { _Pragma("unroll") for (int m = 0; m < 4; ++m) _Pragma("unroll") for (int k = 0; k < 2; ++k) dst[m][k] = *(const PG8_LAS bf16x8*)(lds + PG8_SA(b, h) + aoff + m * 2048 + k * 1024); } while (0)
; #define PG8_LDB(dst, b, h) do { _Pragma("unroll") for (int n = 0; n < 2; ++n) _Pragma("unroll") for (int k = 0; k < 2; ++k) dst[n][k] = *(const PG8_LAS bf16x8*)(lds + PG8_SB(b, h) + boff + n * 2048 + k * 1024); } while (0)
; #define PG8_MMA(ai, bj, At, Bt) do { __builtin_amdgcn_s_setprio(1); _Pragma("unroll") for (int m = 0; m < 4; ++m) _Pragma("unroll") for (int n = 0; n < 2; ++n) _Pragma("unroll") for (int k = 0; k < 2; ++k) \
;         acc[ai][bj][m][n] = __builtin_amdgcn_mfma_f32_16x16x32_bf16(Bt[n][k], At[m][k], acc[ai][bj][m][n], 0, 0, 0); __builtin_amdgcn_s_setprio(0); } while (0)
; #define PG8_WAIT_V(n) asm volatile("s_waitcnt vmcnt(" #n ")" ::: "memory")
; #define PG8_WAIT_L(n) asm volatile("s_waitcnt lgkmcnt(" #n ")" ::: "memory")
; #define PG8_BAR __builtin_amdgcn_s_barrier()
; #define PG8_SCHED __builtin_amdgcn_sched_barrier(0)
; template <class Epi, class Sched, bool ALIGN_EPI = false, bool SP2 = false>
; __device__ __forceinline__ void gemm_phase(PG8_LAS unsigned char* lds, const Gemm g, const Sched& S, const Epi& E) {
;     ...
;             PG8_LDA(At, 0, 1); PG8_STAGE(PG8_SB(0, 0), b2, voffB); PG8_STAGE(PG8_SB(0, 1), b2 + hstep, voffB); PG8_STAGE(PG8_SA(0, 0), a2, voffA);
;             PG8_WAIT_V(8); PG8_WAIT_L(0); PG8_BAR; PG8_MMA(1, 0, At, B0); PG8_MMA(1, 1, At, B1); PG8_BAR; PG8_SCHED;
;             PG8_LDB(B0, 1, 0); PG8_LDB(B1, 1, 1); PG8_SCHED; PG8_LDA(At, 1, 0); PG8_STAGE(PG8_SA(0, 1), a2 + hstep, voffA);
;             PG8_WAIT_V(8); PG8_WAIT_L(0); PG8_BAR; PG8_MMA(0, 0, At, B0); PG8_MMA(0, 1, At, B1); PG8_BAR; PG8_SCHED;
	s_setprio 1
	s_waitcnt lgkmcnt(0)
	v_mfma_f32_16x16x32_bf16 v[68:71], v[104:107], v[196:199], v[68:71]
	v_mfma_f32_16x16x32_bf16 v[60:63], v[144:147], v[196:199], v[60:63]
	v_mfma_f32_16x16x32_bf16 v[52:55], v[104:107], v[218:221], v[52:55]
	s_mov_b32 m0, s44
	v_mfma_f32_16x16x32_bf16 v[44:47], v[144:147], v[218:221], v[44:47]
	global_load_lds_dwordx4 v[242:243], off
	v_mfma_f32_16x16x32_bf16 v[36:39], v[104:107], v[226:229], v[36:39]
	v_mfma_f32_16x16x32_bf16 v[28:31], v[144:147], v[226:229], v[28:31]
	v_mfma_f32_16x16x32_bf16 v[20:23], v[104:107], v[234:237], v[20:23]
	v_mfma_f32_16x16x32_bf16 v[12:15], v[144:147], v[234:237], v[12:15]
	v_mfma_f32_16x16x32_bf16 v[68:71], v[140:143], v[214:217], v[68:71]
	v_mfma_f32_16x16x32_bf16 v[60:63], v[148:151], v[214:217], v[60:63]
	v_mfma_f32_16x16x32_bf16 v[52:55], v[140:143], v[222:225], v[52:55]
	s_mov_b32 m0, s45
	v_mfma_f32_16x16x32_bf16 v[44:47], v[148:151], v[222:225], v[44:47]
	global_load_lds_dwordx4 v[244:245], off
	v_mfma_f32_16x16x32_bf16 v[36:39], v[140:143], v[230:233], v[36:39]
	v_mfma_f32_16x16x32_bf16 v[28:31], v[148:151], v[230:233], v[28:31]
	v_mfma_f32_16x16x32_bf16 v[20:23], v[140:143], v[238:241], v[20:23]
	v_mfma_f32_16x16x32_bf16 v[12:15], v[148:151], v[238:241], v[12:15]
	s_setprio 0
	s_setprio 1
	v_mfma_f32_16x16x32_bf16 v[64:67], v[152:155], v[196:199], v[64:67]
	v_mfma_f32_16x16x32_bf16 v[56:59], v[160:163], v[196:199], v[56:59]
	v_mfma_f32_16x16x32_bf16 v[48:51], v[152:155], v[218:221], v[48:51]
	v_mfma_f32_16x16x32_bf16 v[40:43], v[160:163], v[218:221], v[40:43]
	v_mfma_f32_16x16x32_bf16 v[32:35], v[152:155], v[226:229], v[32:35]
	v_mfma_f32_16x16x32_bf16 v[24:27], v[160:163], v[226:229], v[24:27]
	v_mfma_f32_16x16x32_bf16 v[16:19], v[152:155], v[234:237], v[16:19]
	v_mfma_f32_16x16x32_bf16 v[8:11], v[160:163], v[234:237], v[8:11]
	v_mfma_f32_16x16x32_bf16 v[64:67], v[156:159], v[214:217], v[64:67]
	v_mfma_f32_16x16x32_bf16 v[56:59], v[192:195], v[214:217], v[56:59]
	v_mfma_f32_16x16x32_bf16 v[48:51], v[156:159], v[222:225], v[48:51]
	v_mfma_f32_16x16x32_bf16 v[40:43], v[192:195], v[222:225], v[40:43]
	v_mfma_f32_16x16x32_bf16 v[32:35], v[156:159], v[230:233], v[32:35]
	v_mfma_f32_16x16x32_bf16 v[24:27], v[192:195], v[230:233], v[24:27]
	v_mfma_f32_16x16x32_bf16 v[16:19], v[156:159], v[238:241], v[16:19]
	s_barrier
	v_mfma_f32_16x16x32_bf16 v[8:11], v[192:195], v[238:241], v[8:11]
	s_setprio 0
	s_add_i32 s18, 0, 0x18000
	v_add_u32_e32 v0, s18, v210
	ds_read_b128 v[104:107], v0
	ds_read_b128 v[140:143], v0 offset:1024
	ds_read_b128 v[144:147], v0 offset:2048
	ds_read_b128 v[148:151], v0 offset:3072
	v_add_u32_e32 v0, s33, v210
	ds_read_b128 v[152:155], v0
	ds_read_b128 v[156:159], v0 offset:1024
	ds_read_b128 v[160:163], v0 offset:2048
	ds_read_b128 v[192:195], v0 offset:3072
	s_add_u32 s16, s42, 0x40000
	s_addc_u32 s17, s43, 0
	s_mov_b32 m0, s46
	v_lshl_add_u64 v[246:247], s[16:17], 0, v[184:185]
	ds_read_b128 v[196:199], v212 offset:32768
	ds_read_b128 v[214:217], v212 offset:33792
	ds_read_b128 v[218:221], v212 offset:34816
	ds_read_b128 v[222:225], v212 offset:35840
	ds_read_b128 v[226:229], v212 offset:36864
	ds_read_b128 v[230:233], v212 offset:37888
	ds_read_b128 v[234:237], v212 offset:38912
	ds_read_b128 v[238:241], v212 offset:39936
	global_load_lds_dwordx4 v[246:247], off
	v_lshl_add_u64 v[246:247], s[16:17], 0, v[180:181]
	s_mov_b32 m0, s47
	s_nop 0
	global_load_lds_dwordx4 v[246:247], off
	s_waitcnt vmcnt(8)
	s_waitcnt lgkmcnt(0)
	s_barrier
	s_setprio 1
	s_waitcnt lgkmcnt(0)
	v_mfma_f32_16x16x32_bf16 v[136:139], v[104:107], v[196:199], v[136:139]
	v_mfma_f32_16x16x32_bf16 v[128:131], v[144:147], v[196:199], v[128:131]
	v_mfma_f32_16x16x32_bf16 v[120:123], v[104:107], v[218:221], v[120:123]
	v_mfma_f32_16x16x32_bf16 v[112:115], v[144:147], v[218:221], v[112:115]
	v_mfma_f32_16x16x32_bf16 v[100:103], v[104:107], v[226:229], v[100:103]
	v_mfma_f32_16x16x32_bf16 v[92:95], v[144:147], v[226:229], v[92:95]
	v_mfma_f32_16x16x32_bf16 v[84:87], v[104:107], v[234:237], v[84:87]
	v_mfma_f32_16x16x32_bf16 v[76:79], v[144:147], v[234:237], v[76:79]
	v_mfma_f32_16x16x32_bf16 v[136:139], v[140:143], v[214:217], v[136:139]
	v_mfma_f32_16x16x32_bf16 v[128:131], v[148:151], v[214:217], v[128:131]
	v_mfma_f32_16x16x32_bf16 v[120:123], v[140:143], v[222:225], v[120:123]
	v_mfma_f32_16x16x32_bf16 v[112:115], v[148:151], v[222:225], v[112:115]
	v_mfma_f32_16x16x32_bf16 v[100:103], v[140:143], v[230:233], v[100:103]
	v_mfma_f32_16x16x32_bf16 v[92:95], v[148:151], v[230:233], v[92:95]
	v_mfma_f32_16x16x32_bf16 v[84:87], v[140:143], v[238:241], v[84:87]
	v_mfma_f32_16x16x32_bf16 v[76:79], v[148:151], v[238:241], v[76:79]
	s_setprio 0
	s_setprio 1
	v_mfma_f32_16x16x32_bf16 v[132:135], v[152:155], v[196:199], v[132:135]
	v_mfma_f32_16x16x32_bf16 v[124:127], v[160:163], v[196:199], v[124:127]
	v_mfma_f32_16x16x32_bf16 v[116:119], v[152:155], v[218:221], v[116:119]
	v_mfma_f32_16x16x32_bf16 v[108:111], v[160:163], v[218:221], v[108:111]
	v_mfma_f32_16x16x32_bf16 v[96:99], v[152:155], v[226:229], v[96:99]
	v_mfma_f32_16x16x32_bf16 v[88:91], v[160:163], v[226:229], v[88:91]
	v_mfma_f32_16x16x32_bf16 v[80:83], v[152:155], v[234:237], v[80:83]
	v_mfma_f32_16x16x32_bf16 v[72:75], v[160:163], v[234:237], v[72:75]
	v_mfma_f32_16x16x32_bf16 v[132:135], v[156:159], v[214:217], v[132:135]
	v_mfma_f32_16x16x32_bf16 v[124:127], v[192:195], v[214:217], v[124:127]
	v_mfma_f32_16x16x32_bf16 v[116:119], v[156:159], v[222:225], v[116:119]
	v_mfma_f32_16x16x32_bf16 v[108:111], v[192:195], v[222:225], v[108:111]
	v_mfma_f32_16x16x32_bf16 v[96:99], v[156:159], v[230:233], v[96:99]
	v_mfma_f32_16x16x32_bf16 v[88:91], v[192:195], v[230:233], v[88:91]
	v_mfma_f32_16x16x32_bf16 v[80:83], v[156:159], v[238:241], v[80:83]
	s_barrier
; #define PG8_STAGE(bufoff, gbase, voff) do { _Pragma("unroll") for (int _i = 0; _i < 2; ++_i) \
;         __builtin_amdgcn_global_load_lds((const unsigned*)((const char*)(gbase) + (voff)[_i]), (PG8_LAS unsigned*)(lds + (bufoff) + ldsw + _i * 8192), 16, 0, 0); } while (0)
; #define PG8_LDA(dst, b, h) do { _Pragma("unroll") for (int m = 0; m < 4; ++m) _Pragma("unroll") for (int k = 0; k < 2; ++k) dst[m][k] = *(const PG8_LAS bf16x8*)(lds + PG8_SA(b, h) + aoff + m * 2048 + k * 1024); } while (0)
; #define PG8_MMA(ai, bj, At, Bt) do { __builtin_amdgcn_s_setprio(1); _Pragma("unroll") for (int m = 0; m < 4; ++m) _Pragma("unroll") for (int n = 0; n < 2; ++n) _Pragma("unroll") for (int k = 0; k < 2; ++k) \
;         acc[ai][bj][m][n] = __builtin_amdgcn_mfma_f32_16x16x32_bf16(Bt[n][k], At[m][k], acc[ai][bj][m][n], 0, 0, 0); __builtin_amdgcn_s_setprio(0); } while (0)
; #define PG8_WAIT_V(n) asm volatile("s_waitcnt vmcnt(" #n ")" ::: "memory")
; #define PG8_WAIT_L(n) asm volatile("s_waitcnt lgkmcnt(" #n ")" ::: "memory")
; #define PG8_BAR __builtin_amdgcn_s_barrier()
; #define PG8_SCHED __builtin_amdgcn_sched_barrier(0)
; template <class Epi, class Sched, bool ALIGN_EPI = false, bool SP2 = false>
; __device__ __forceinline__ void gemm_phase(PG8_LAS unsigned char* lds, const Gemm g, const Sched& S, const Epi& E) {
;     ...
;             PG8_WAIT_V(8); PG8_WAIT_L(0); PG8_BAR; PG8_MMA(0, 0, At, B0); PG8_MMA(0, 1, At, B1); PG8_BAR; PG8_SCHED;
;             PG8_LDA(At, 1, 1); PG8_STAGE(PG8_SB(1, 0), b3, voffB); PG8_STAGE(PG8_SB(1, 1), b3 + hstep, voffB); PG8_STAGE(PG8_SA(1, 0), a3, voffA);
;             PG8_WAIT_V(8); PG8_WAIT_L(0); PG8_BAR; PG8_MMA(1, 0, At, B0); PG8_MMA(1, 1, At, B1); PG8_BAR; PG8_SCHED;
;     ...
;         if constexpr (ALIGN_EPI) { if (wr == 0) PG8_BAR; }
;         if constexpr (!Epi::AFTER_DRAIN) { if (wr == 0) __builtin_amdgcn_s_setprio(1);
	v_mfma_f32_16x16x32_bf16 v[72:75], v[192:195], v[238:241], v[72:75]
	s_setprio 0
	s_add_i32 s16, s18, s36
	v_lshl_add_u64 v[2:3], v[2:3], 0, s[20:21]
	s_mov_b32 m0, s16
	ds_read_b128 v[196:199], v212 offset:49152
	ds_read_b128 v[214:217], v212 offset:50176
	ds_read_b128 v[218:221], v212 offset:51200
	ds_read_b128 v[222:225], v212 offset:52224
	ds_read_b128 v[226:229], v212 offset:53248
	ds_read_b128 v[230:233], v212 offset:54272
	ds_read_b128 v[234:237], v212 offset:55296
	ds_read_b128 v[238:241], v212 offset:56320
	global_load_lds_dwordx4 v[2:3], off
	s_add_i32 m0, s16, 0x2000
	s_add_u32 s16, s40, 0x40080
	v_lshl_add_u64 v[2:3], v[200:201], 0, s[20:21]
	s_addc_u32 s17, s41, 0
	s_add_i32 s18, s33, s36
	global_load_lds_dwordx4 v[2:3], off
	v_lshl_add_u64 v[2:3], s[16:17], 0, v[182:183]
	s_mov_b32 m0, s18
	s_nop 0
	global_load_lds_dwordx4 v[2:3], off
	v_lshl_add_u64 v[2:3], s[16:17], 0, v[178:179]
	s_add_i32 m0, s18, 0x2000
	s_nop 0
	global_load_lds_dwordx4 v[2:3], off
	v_lshl_add_u64 v[2:3], v[242:243], 0, s[20:21]
	v_lshl_add_u64 v[244:245], v[244:245], 0, s[20:21]
	s_waitcnt vmcnt(6)
	s_waitcnt lgkmcnt(0)
	s_barrier
	s_setprio 1
	s_waitcnt lgkmcnt(0)
	v_mfma_f32_16x16x32_bf16 v[68:71], v[104:107], v[196:199], v[68:71]
	v_mfma_f32_16x16x32_bf16 v[60:63], v[144:147], v[196:199], v[60:63]
	v_mfma_f32_16x16x32_bf16 v[52:55], v[104:107], v[218:221], v[52:55]
	s_mov_b32 m0, s48
	v_mfma_f32_16x16x32_bf16 v[44:47], v[144:147], v[218:221], v[44:47]
	global_load_lds_dwordx4 v[2:3], off
	v_mfma_f32_16x16x32_bf16 v[36:39], v[104:107], v[226:229], v[36:39]
	v_mfma_f32_16x16x32_bf16 v[28:31], v[144:147], v[226:229], v[28:31]
	v_mfma_f32_16x16x32_bf16 v[20:23], v[104:107], v[234:237], v[20:23]
	v_mfma_f32_16x16x32_bf16 v[12:15], v[144:147], v[234:237], v[12:15]
	v_mfma_f32_16x16x32_bf16 v[68:71], v[140:143], v[214:217], v[68:71]
	v_mfma_f32_16x16x32_bf16 v[60:63], v[148:151], v[214:217], v[60:63]
	v_mfma_f32_16x16x32_bf16 v[52:55], v[140:143], v[222:225], v[52:55]
	s_mov_b32 m0, s49
	v_mfma_f32_16x16x32_bf16 v[44:47], v[148:151], v[222:225], v[44:47]
	global_load_lds_dwordx4 v[244:245], off
	v_mfma_f32_16x16x32_bf16 v[36:39], v[140:143], v[230:233], v[36:39]
	v_mfma_f32_16x16x32_bf16 v[28:31], v[148:151], v[230:233], v[28:31]
	v_mfma_f32_16x16x32_bf16 v[20:23], v[140:143], v[238:241], v[20:23]
	v_mfma_f32_16x16x32_bf16 v[12:15], v[148:151], v[238:241], v[12:15]
	s_setprio 0
	s_setprio 1
	v_mfma_f32_16x16x32_bf16 v[64:67], v[152:155], v[196:199], v[64:67]
	v_mfma_f32_16x16x32_bf16 v[56:59], v[160:163], v[196:199], v[56:59]
	v_mfma_f32_16x16x32_bf16 v[48:51], v[152:155], v[218:221], v[48:51]
	v_mfma_f32_16x16x32_bf16 v[40:43], v[160:163], v[218:221], v[40:43]
	v_mfma_f32_16x16x32_bf16 v[32:35], v[152:155], v[226:229], v[32:35]
	v_mfma_f32_16x16x32_bf16 v[24:27], v[160:163], v[226:229], v[24:27]
	v_mfma_f32_16x16x32_bf16 v[16:19], v[152:155], v[234:237], v[16:19]
	v_mfma_f32_16x16x32_bf16 v[8:11], v[160:163], v[234:237], v[8:11]
	v_mfma_f32_16x16x32_bf16 v[64:67], v[156:159], v[214:217], v[64:67]
	v_mfma_f32_16x16x32_bf16 v[56:59], v[192:195], v[214:217], v[56:59]
	v_mfma_f32_16x16x32_bf16 v[48:51], v[156:159], v[222:225], v[48:51]
	v_mfma_f32_16x16x32_bf16 v[40:43], v[192:195], v[222:225], v[40:43]
	v_mfma_f32_16x16x32_bf16 v[32:35], v[156:159], v[230:233], v[32:35]
	v_mfma_f32_16x16x32_bf16 v[24:27], v[192:195], v[230:233], v[24:27]
	v_mfma_f32_16x16x32_bf16 v[16:19], v[156:159], v[238:241], v[16:19]
	s_barrier
	v_mfma_f32_16x16x32_bf16 v[8:11], v[192:195], v[238:241], v[8:11]
	s_setprio 0
	s_add_i32 s55, s55, 2
	s_add_u32 s8, s8, 0x100
	s_addc_u32 s9, s9, 0
	s_add_u32 s53, s53, 0x100
	s_addc_u32 s54, s54, 0
	s_cmp_gt_u32 s55, 13
	s_cbranch_scc0 .LBB0_257
	s_and_b64 vcc, exec, s[10:11]
	s_cbranch_vccz .LBB0_260
	s_barrier
	s_setprio 1
